# attention tile loop: LDS-DMA source addresses from 4 precomputed per-lane offsets + SGPR bases instead of ~65 VALU per step
# speedup vs baseline: 1.0061x; 1.0061x over previous
.LBB0_178:
	s_or_b64 exec, exec, s[6:7]
	s_waitcnt lgkmcnt(0)
	s_barrier
	v_mbcnt_lo_u32_b32 v2, -1, 0
	v_mbcnt_hi_u32_b32 v2, -1, v2
	s_load_dwordx2 s[6:7], s[0:1], 0x98
	s_waitcnt lgkmcnt(0)
	s_load_dwordx2 s[8:9], s[0:1], 16
	s_waitcnt lgkmcnt(0)
	s_load_dwordx2 s[10:11], s[0:1], 24
	s_waitcnt lgkmcnt(0)
	s_load_dwordx2 s[12:13], s[0:1], 32
	s_waitcnt lgkmcnt(0)
	s_load_dwordx2 s[14:15], s[0:1], 40
	s_waitcnt lgkmcnt(0)
	s_nop 0
	v_ashrrev_i32_e32 v3, 31, v2
	v_lshlrev_b64 v[4:5], 2, v[2:3]
	v_lshl_add_u64 v[6:7], s[8:9], 0, v[4:5]
	v_lshl_add_u64 v[8:9], s[10:11], 0, v[4:5]
	global_load_dword v10, v[6:7], off
	global_load_dword v11, v[6:7], off offset:256
	global_load_dword v12, v[8:9], off
	global_load_dword v13, v[8:9], off offset:256
	v_lshl_add_u64 v[6:7], s[12:13], 0, v[4:5]
	v_lshl_add_u64 v[4:5], s[14:15], 0, v[4:5]
	global_load_dword v8, v[6:7], off
	global_load_dword v9, v[6:7], off offset:256
	global_load_dword v14, v[4:5], off
	global_load_dword v15, v[4:5], off offset:256
	s_abs_i32 s13, s24
	v_cvt_f32_u32_e32 v3, s13
	v_lshlrev_b32_e32 v2, 2, v2
	v_xor_b32_e32 v6, 4, v2
	v_xor_b32_e32 v7, 8, v2
	v_xor_b32_e32 v16, 16, v2
	v_xor_b32_e32 v17, 32, v2
	v_xor_b32_e32 v18, 64, v2
	v_xor_b32_e32 v19, 0x80, v2
	v_rcp_iflag_f32_e32 v20, v3
	v_readfirstlane_b32 s10, v0
	s_lshr_b32 s10, s10, 4
	s_and_b32 s10, s10, 0xffffffc
	s_add_i32 s10, s10, 0
	s_mov_b32 s8, 0x3fb8aa3b
	s_add_i32 s29, s10, 0x20c00
	s_sub_i32 s15, 0, s13
	s_sub_i32 s11, s24, s17
	s_add_i32 s14, s11, 0x1ff
	s_sub_i32 s11, 0xfffffe01, s11
	s_xor_b32 s28, s14, s24
	s_max_i32 s14, s14, s11
	s_mov_b32 s9, 0xc2ce8ed0
	s_mov_b32 s12, 0x42b17218
	v_mov_b32_e32 v1, 0x7f800000
	s_ashr_i32 s28, s28, 31
	s_load_dwordx2 s[10:11], s[0:1], 48
	s_waitcnt lgkmcnt(0)
	s_mov_b32 s25, 0
	s_waitcnt vmcnt(4)
	v_pk_mul_f32 v[2:3], v[10:11], v[12:13]
	s_nop 0
	v_add_f32_e32 v2, v2, v3
	s_waitcnt vmcnt(0)
	v_pk_mul_f32 v[4:5], v[8:9], v[14:15]
	s_nop 0
	v_add_f32_e32 v3, v4, v5
	ds_bpermute_b32 v4, v6, v2
	ds_bpermute_b32 v5, v6, v3
	v_mul_f32_e32 v8, 0x4f7ffffe, v20
	v_cvt_u32_f32_e32 v8, v8
	v_mov_b32_e32 v6, s29
	s_waitcnt lgkmcnt(1)
	v_add_f32_e32 v2, v2, v4
	s_waitcnt lgkmcnt(0)
	v_add_f32_e32 v3, v3, v5
	ds_bpermute_b32 v4, v7, v2
	ds_bpermute_b32 v5, v7, v3
	v_readfirstlane_b32 s29, v8
	s_mul_i32 s15, s15, s29
	s_mul_hi_u32 s15, s29, s15
	s_waitcnt lgkmcnt(1)
	v_add_f32_e32 v2, v2, v4
	s_waitcnt lgkmcnt(0)
	v_add_f32_e32 v3, v3, v5
	ds_bpermute_b32 v4, v16, v2
	ds_bpermute_b32 v5, v16, v3
	s_add_i32 s29, s29, s15
	s_mul_hi_u32 s15, s14, s29
	s_mul_i32 s29, s15, s13
	s_waitcnt lgkmcnt(1)
	v_add_f32_e32 v2, v2, v4
	s_waitcnt lgkmcnt(0)
	v_add_f32_e32 v3, v3, v5
	ds_bpermute_b32 v4, v17, v2
	ds_bpermute_b32 v5, v17, v3
	s_sub_i32 s14, s14, s29
	s_add_i32 s30, s15, 1
	s_sub_i32 s29, s14, s13
	s_waitcnt lgkmcnt(1)
	v_add_f32_e32 v2, v2, v4
	s_waitcnt lgkmcnt(0)
	v_add_f32_e32 v3, v3, v5
	ds_bpermute_b32 v4, v18, v2
	ds_bpermute_b32 v5, v18, v3
	s_cmp_ge_u32 s14, s13
	s_cselect_b32 s15, s30, s15
	s_cselect_b32 s14, s29, s14
	s_waitcnt lgkmcnt(1)
	v_add_f32_e32 v2, v2, v4
	s_waitcnt lgkmcnt(0)
	v_add_f32_e32 v3, v3, v5
	ds_bpermute_b32 v4, v19, v2
	ds_bpermute_b32 v5, v19, v3
	s_add_i32 s29, s15, 1
	s_cmp_ge_u32 s14, s13
	s_cselect_b32 s13, s29, s15
	s_waitcnt lgkmcnt(1)
	v_add_f32_e32 v2, v2, v4
	s_waitcnt lgkmcnt(0)
	v_add_f32_e32 v3, v3, v5
	v_mul_f32_e32 v4, 0x3fb8aa3b, v2
	v_mul_f32_e32 v5, 0x3fb8aa3b, v3
	v_fma_f32 v7, v2, s8, -v4
	v_rndne_f32_e32 v8, v4
	v_fma_f32 v9, v3, s8, -v5
	v_rndne_f32_e32 v10, v5
	v_fmac_f32_e32 v7, 0x32a5705f, v2
	v_sub_f32_e32 v4, v4, v8
	v_fmac_f32_e32 v9, 0x32a5705f, v3
	v_sub_f32_e32 v5, v5, v10
	v_add_f32_e32 v4, v4, v7
	v_cvt_i32_f32_e32 v8, v8
	v_add_f32_e32 v5, v5, v9
	v_exp_f32_e32 v4, v4
	v_cvt_i32_f32_e32 v10, v10
	v_exp_f32_e32 v5, v5
	v_cmp_ngt_f32_e32 vcc, s9, v2
	v_ldexp_f32 v4, v4, v8
	s_xor_b32 s8, s13, s28
	v_ldexp_f32 v5, v5, v10
	v_cndmask_b32_e32 v4, 0, v4, vcc
	v_cmp_ngt_f32_e32 vcc, s9, v3
	s_sub_i32 s8, s8, s28
	s_cmp_lt_i32 s8, 1
	v_cndmask_b32_e32 v5, 0, v5, vcc
	v_cmp_nlt_f32_e32 vcc, s12, v2
	s_nop 1
	v_cndmask_b32_e32 v2, v1, v4, vcc
	v_cmp_nlt_f32_e32 vcc, s12, v3
	s_nop 1
	v_cndmask_b32_e32 v1, v1, v5, vcc
	v_sub_f32_e32 v1, v2, v1
	v_add_f32_e32 v1, 0x3e4ccccd, v1
	ds_write_b32 v6, v1
	s_waitcnt lgkmcnt(0)
	s_cbranch_scc1 .LBB0_463
	s_add_u32 s38, s6, 0x16100000
	s_addc_u32 s39, s7, 0
	s_add_u32 s40, s6, 0x3e100000
	s_addc_u32 s41, s7, 0
	s_lshl_b32 s8, s8, 1
	s_max_i32 s42, s8, 1
	s_add_u32 s43, s6, 0x16601100
	s_mov_b32 s14, 0xffd7ff00
	s_mov_b32 s28, 0xffd80000
	s_movk_i32 s30, 0xff00
	s_addc_u32 s44, s7, 0
	s_movk_i32 s45, 0x5000
	s_mov_b64 s[12:13], 0x100
	v_mov_b32_e32 v223, 0
	s_brev_b32 s46, -2
	s_add_i32 s47, 0, 0x18000
	s_mov_b32 s15, -1
	s_mov_b32 s29, -1
	s_movk_i32 s48, 0x70
	s_brev_b32 s49, 1
	s_mov_b32 s50, 0x41000000
	s_movk_i32 s51, 0x100
	s_mov_b32 s31, -1
	s_movk_i32 s52, 0xc000
	v_mov_b32_e32 v1, 0x3727c5ac
	s_mov_b32 s53, 0xf800000
	v_mov_b32_e32 v224, 0x260
	v_mov_b32_e32 v225, 0xff800000
	v_mbcnt_lo_u32_b32 v255, -1, 0
	v_mbcnt_hi_u32_b32 v255, -1, v255
	v_lshrrev_b32_e32 v251, 4, v255
	v_and_b32_e32 v252, 15, v255
	v_xor_b32_e32 v252, v252, v251
	v_lshlrev_b32_e32 v252, 4, v252
	v_mul_u32_u24_e32 v251, 0xa000, v251
	v_add_u32_e32 v251, v251, v252
	s_mul_i32 s98, s19, 0x50000
	v_add_u32_e32 v251, s98, v251
	v_xor_b32_e32 v252, 64, v251
	v_add_u32_e32 v252, 0x28000, v252
	v_bfe_u32 v253, v255, 2, 3
	s_and_b32 s98, s19, 1
	s_lshl_b32 s98, s98, 4
	v_or_b32_e32 v253, s98, v253
	v_mul_u32_u24_e32 v253, 0xa000, v253
	v_lshrrev_b32_e32 v254, 5, v255
	v_lshlrev_b32_e32 v254, 6, v254
	v_add_u32_e32 v253, v253, v254
	v_bfe_u32 v254, v255, 4, 1
	v_xor_b32_e32 v254, v254, v255
	v_and_b32_e32 v254, 3, v254
	v_lshlrev_b32_e32 v254, 4, v254
	v_add_u32_e32 v253, v253, v254
	v_xor_b32_e32 v254, 32, v253
	v_add_u32_e32 v254, 0x50000, v254
	s_branch .LBB0_182

.LBB0_185:
	s_waitcnt vmcnt(0)
	s_barrier
	v_mbcnt_lo_u32_b32 v192, -1, 0
	v_mbcnt_hi_u32_b32 v192, -1, v192
	s_add_i32 s35, 0, 0x10000
	s_add_i32 s37, s35, s61
	s_add_i32 s92, s37, 0x4000
	s_add_u32 s98, s8, s14
	s_addc_u32 s99, s9, s15
	s_add_u32 s100, s8, s28
	s_addc_u32 s101, s9, s29
	s_mov_b32 m0, s37
	s_add_i32 s35, s35, s65
	global_load_lds_dwordx4 v251, s[98:99]
	s_mov_b32 m0, s92
	s_add_i32 s93, s35, 0x4000
	global_load_lds_dwordx4 v251, s[100:101]
	s_mov_b32 m0, s35
	s_add_i32 s36, s68, s79
	global_load_lds_dwordx4 v252, s[98:99]
	s_mov_b32 m0, s93
	s_add_i32 s90, s36, 64
	global_load_lds_dwordx4 v252, s[100:101]
	s_add_i32 s34, s79, 63
	s_mul_hi_i32 s91, s90, 0xa000
	s_mul_i32 s90, s90, 0xa000
	s_add_u32 s90, s82, s90
	s_addc_u32 s91, s83, s91
	s_add_u32 s98, s90, 0x80
	s_addc_u32 s99, s91, 0
	s_add_i32 s94, s47, s70
	s_mov_b32 m0, s94
	s_add_i32 s95, s94, 0x400
	global_load_lds_dwordx4 v253, s[90:91]
	s_mov_b32 m0, s95
	s_add_i32 s96, s47, s74
	global_load_lds_dwordx4 v253, s[98:99]
	s_mov_b32 m0, s96
	s_add_i32 s97, s47, s77
	global_load_lds_dwordx4 v254, s[90:91]
	s_mov_b32 m0, s97
	v_ashrrev_i32_e32 v188, 5, v192
	global_load_lds_dwordx4 v254, s[98:99]
	v_and_b32_e32 v193, 31, v192
	v_lshlrev_b32_e32 v189, 4, v192
	v_lshlrev_b32_e32 v191, 4, v188
	v_lshlrev_b32_e32 v190, 8, v193
	v_bitop3_b32 v2, v189, v191, s48 bitop3:0x6c
	v_add3_u32 v6, s84, v2, v190
	ds_read_b128 v[2:5], v6
	ds_read_b128 v[194:197], v6 offset:128
	s_waitcnt lgkmcnt(0)
	v_mfma_f32_32x32x16_bf16 v[18:33], v[2:5], v[34:37], 0
	ds_read_b128 v[2:5], v6 offset:8192
	ds_read_b128 v[198:201], v6 offset:8320
	v_add_u32_e32 v7, 32, v191
	v_bitop3_b32 v7, v7, v189, s48 bitop3:0x78
	v_add3_u32 v210, s84, v7, v190
	ds_read_b128 v[202:205], v210
	ds_read_b128 v[206:209], v210 offset:128
	v_add_u32_e32 v211, 64, v191
	s_waitcnt lgkmcnt(0)
	v_mfma_f32_32x32x16_bf16 v[18:33], v[202:205], v[38:41], v[18:33]
	ds_read_b128 v[202:205], v210 offset:8192
	v_bitop3_b32 v211, v211, v189, s48 bitop3:0x78
	v_add3_u32 v218, s84, v211, v190
	ds_read_b128 v[210:213], v210 offset:8320
	v_add_u32_e32 v191, 0x60, v191
	v_bitop3_b32 v191, v191, v189, s48 bitop3:0x78
	v_add3_u32 v190, s84, v191, v190
	v_mfma_f32_32x32x16_bf16 v[2:17], v[2:5], v[34:37], 0
	v_add_u32_e32 v189, s81, v189
	s_cmp_le_u32 s34, s59
	s_waitcnt lgkmcnt(0)
	v_mfma_f32_32x32x16_bf16 v[2:17], v[202:205], v[38:41], v[2:17]
	ds_read_b128 v[202:205], v218
	ds_read_b128 v[214:217], v218 offset:128
	s_waitcnt lgkmcnt(0)
	v_mfma_f32_32x32x16_bf16 v[18:33], v[202:205], v[42:45], v[18:33]
	ds_read_b128 v[202:205], v218 offset:8192
	ds_read_b128 v[218:221], v218 offset:8320
	s_waitcnt lgkmcnt(0)
	v_mfma_f32_32x32x16_bf16 v[2:17], v[202:205], v[42:45], v[2:17]
	ds_read_b128 v[202:205], v190
	ds_read_b128 v[226:229], v190 offset:128
	s_waitcnt lgkmcnt(0)
	v_mfma_f32_32x32x16_bf16 v[18:33], v[202:205], v[46:49], v[18:33]
	ds_read_b128 v[202:205], v190 offset:8192
	ds_read_b128 v[230:233], v190 offset:8320
	s_waitcnt lgkmcnt(0)
	v_mfma_f32_32x32x16_bf16 v[2:17], v[202:205], v[46:49], v[2:17]
	v_mfma_f32_32x32x16_bf16 v[18:33], v[194:197], v[50:53], v[18:33]
	v_mfma_f32_32x32x16_bf16 v[2:17], v[198:201], v[50:53], v[2:17]
	ds_read_b128 v[194:197], v189
	ds_read_b128 v[198:201], v189 offset:1024
	v_mfma_f32_32x32x16_bf16 v[18:33], v[206:209], v[54:57], v[18:33]
	v_mfma_f32_32x32x16_bf16 v[2:17], v[210:213], v[54:57], v[2:17]
	s_waitcnt lgkmcnt(0)
	v_mfma_f32_32x32x16_bf16 v[18:33], v[214:217], v[194:197], v[18:33]
	v_mfma_f32_32x32x16_bf16 v[2:17], v[218:221], v[194:197], v[2:17]
	v_mfma_f32_32x32x16_bf16 v[18:33], v[226:229], v[198:201], v[18:33]
	v_mfma_f32_32x32x16_bf16 v[2:17], v[230:233], v[198:201], v[2:17]
	s_cbranch_scc1 .LBB0_187
	v_lshlrev_b32_e32 v188, 2, v188
	v_sub_u32_e32 v188, v193, v188
	v_add_u32_e32 v188, s86, v188
	v_add_u32_e32 v189, 0x80000001, v188
	v_cmp_gt_u32_e32 vcc, s46, v189
	s_nop 4
	v_cndmask_b32_e32 v18, v225, v18, vcc
	v_cmp_lt_i32_e32 vcc, 31, v189
	s_nop 1
	v_cndmask_b32_e32 v2, v225, v2, vcc
	v_cmp_lt_i32_e32 vcc, 0, v189
	v_subrev_u32_e32 v189, 31, v188
	s_nop 0
	v_cndmask_b32_e32 v19, v225, v19, vcc
	v_cmp_lt_u32_e32 vcc, s49, v189
	v_subrev_u32_e32 v189, 32, v188
	s_nop 0
	v_cndmask_b32_e32 v3, v225, v3, vcc
	v_cmp_lt_u32_e32 vcc, s49, v188
	s_nop 1
	v_cndmask_b32_e32 v20, v225, v20, vcc
	v_cmp_lt_u32_e32 vcc, s49, v189
	v_add_u32_e32 v189, -1, v188
	s_nop 0
	v_cndmask_b32_e32 v4, v225, v4, vcc
	v_cmp_lt_u32_e32 vcc, s49, v189
	v_subrev_u32_e32 v189, 33, v188
	s_nop 0
	v_cndmask_b32_e32 v21, v225, v21, vcc
	v_cmp_lt_u32_e32 vcc, s49, v189
	v_add_u32_e32 v189, -6, v188
	s_nop 0
	v_cndmask_b32_e32 v5, v225, v5, vcc
	v_cmp_lt_u32_e32 vcc, s49, v189
	v_subrev_u32_e32 v189, 38, v188
	s_nop 0
	v_cndmask_b32_e32 v22, v225, v22, vcc
	v_cmp_lt_u32_e32 vcc, s49, v189
	v_add_u32_e32 v189, -7, v188
	s_nop 0
	v_cndmask_b32_e32 v6, v225, v6, vcc
	v_cmp_lt_u32_e32 vcc, s49, v189
	v_subrev_u32_e32 v189, 39, v188
	s_nop 0
	v_cndmask_b32_e32 v23, v225, v23, vcc
	v_cmp_lt_u32_e32 vcc, s49, v189
	v_add_u32_e32 v189, -8, v188
	s_nop 0
	v_cndmask_b32_e32 v7, v225, v7, vcc
	v_cmp_lt_u32_e32 vcc, s49, v189
	v_subrev_u32_e32 v189, 40, v188
	s_nop 0
	v_cndmask_b32_e32 v24, v225, v24, vcc
	v_cmp_lt_u32_e32 vcc, s49, v189
	v_add_u32_e32 v189, -9, v188
	s_nop 0
	v_cndmask_b32_e32 v8, v225, v8, vcc
	v_cmp_lt_u32_e32 vcc, s49, v189
	v_subrev_u32_e32 v189, 41, v188
	s_nop 0
	v_cndmask_b32_e32 v25, v225, v25, vcc
	v_cmp_lt_u32_e32 vcc, s49, v189
	v_add_u32_e32 v189, -14, v188
	s_nop 0
	v_cndmask_b32_e32 v9, v225, v9, vcc
	v_cmp_lt_u32_e32 vcc, s49, v189
	v_subrev_u32_e32 v189, 46, v188
	s_nop 0
	v_cndmask_b32_e32 v26, v225, v26, vcc
	v_cmp_lt_u32_e32 vcc, s49, v189
	v_add_u32_e32 v189, -15, v188
	s_nop 0
	v_cndmask_b32_e32 v10, v225, v10, vcc
	v_cmp_lt_u32_e32 vcc, s49, v189
	v_subrev_u32_e32 v189, 47, v188
	s_nop 0
	v_cndmask_b32_e32 v27, v225, v27, vcc
	v_cmp_lt_u32_e32 vcc, s49, v189
	v_add_u32_e32 v189, -16, v188
	s_nop 0
	v_cndmask_b32_e32 v11, v225, v11, vcc
	v_cmp_lt_u32_e32 vcc, s49, v189
	v_subrev_u32_e32 v189, 48, v188
	s_nop 0
	v_cndmask_b32_e32 v28, v225, v28, vcc
	v_cmp_lt_u32_e32 vcc, s49, v189
	v_subrev_u32_e32 v189, 17, v188
	s_nop 0
	v_cndmask_b32_e32 v12, v225, v12, vcc
	v_cmp_lt_u32_e32 vcc, s49, v189
	v_subrev_u32_e32 v189, 49, v188
	s_nop 0
	v_cndmask_b32_e32 v29, v225, v29, vcc
	v_cmp_lt_u32_e32 vcc, s49, v189
	v_subrev_u32_e32 v189, 22, v188
	s_nop 0
	v_cndmask_b32_e32 v13, v225, v13, vcc
	v_cmp_lt_u32_e32 vcc, s49, v189
	v_subrev_u32_e32 v189, 54, v188
	s_nop 0
	v_cndmask_b32_e32 v30, v225, v30, vcc
	v_cmp_lt_u32_e32 vcc, s49, v189
	v_subrev_u32_e32 v189, 23, v188
	s_nop 0
	v_cndmask_b32_e32 v14, v225, v14, vcc
	v_cmp_lt_u32_e32 vcc, s49, v189
	v_subrev_u32_e32 v189, 55, v188
	s_nop 0
	v_cndmask_b32_e32 v31, v225, v31, vcc
	v_cmp_lt_u32_e32 vcc, s49, v189
	v_subrev_u32_e32 v189, 24, v188
	s_nop 0
	v_cndmask_b32_e32 v15, v225, v15, vcc
	v_cmp_lt_u32_e32 vcc, s49, v189
	v_subrev_u32_e32 v189, 56, v188
	s_nop 0
	v_cndmask_b32_e32 v32, v225, v32, vcc
	v_cmp_lt_u32_e32 vcc, s49, v189
	v_subrev_u32_e32 v189, 25, v188
	v_subrev_u32_e32 v188, 57, v188
	v_cndmask_b32_e32 v16, v225, v16, vcc
	v_cmp_lt_u32_e32 vcc, s49, v189
	s_nop 1
	v_cndmask_b32_e32 v33, v225, v33, vcc
	v_cmp_lt_u32_e32 vcc, s49, v188
	s_nop 1
	v_cndmask_b32_e32 v17, v225, v17, vcc

.LBB0_192:
	s_cmp_lg_u32 0, -1
	v_lshrrev_b32_e32 v18, 3, v192
	v_ashrrev_i32_e32 v19, 5, v192
	v_and_or_b32 v18, v18, 2, v19
	v_lshlrev_b32_e32 v19, 1, v19
	v_lshrrev_b32_e32 v20, 1, v192
	v_bfe_u32 v21, v192, 1, 1
	v_and_b32_e32 v19, 2, v19
	v_and_b32_e32 v22, 12, v192
	v_or3_b32 v21, v22, v19, v21
	v_bitop3_b32 v19, v19, v20, 1 bitop3:0x72
	v_lshlrev_b32_e32 v18, 11, v18
	v_lshlrev_b32_e32 v23, 3, v192
	v_or_b32_e32 v19, v19, v22
	s_cselect_b32 s34, 0, 0
	v_and_b32_e32 v23, 8, v23
	v_lshl_or_b32 v19, v19, 4, v18
	s_add_i32 s34, s34, 0x8000
	v_lshlrev_b32_e32 v21, 4, v21
	v_or3_b32 v19, v19, v23, s51
	v_add_u32_e32 v20, s34, v23
	s_waitcnt lgkmcnt(0)
	v_add3_u32 v220, v20, v18, v21
	v_add_u32_e32 v221, s34, v19
	ds_read_b64_tr_b16 v[18:19], v220 offset:0
	ds_read_b64_tr_b16 v[20:21], v221 offset:0
	v_xor_b32_e32 v222, 32, v220
	ds_read_b64_tr_b16 v[22:23], v222 offset:0
	v_xor_b32_e32 v250, 32, v221
	ds_read_b64_tr_b16 v[24:25], v250 offset:0
	ds_read_b64_tr_b16 v[26:27], v220 offset:0x200
	ds_read_b64_tr_b16 v[28:29], v221 offset:0x200
	s_waitcnt lgkmcnt(4)
	v_permlane16_swap_b32_e32 v10, v14
	v_permlane16_swap_b32_e32 v11, v15
	v_permlane16_swap_b32_e32 v12, v16
	v_permlane16_swap_b32_e32 v13, v17
	v_permlane16_swap_b32_e32 v2, v6
	v_permlane16_swap_b32_e32 v3, v7
	v_permlane16_swap_b32_e32 v4, v8
	v_permlane16_swap_b32_e32 v5, v9
	v_mfma_f32_16x16x32_bf16 v[30:33], v[10:13], v[18:21], v[58:61]
	v_mfma_f32_16x16x32_bf16 v[18:21], v[14:17], v[18:21], v[178:181]
	ds_read_b64_tr_b16 v[58:59], v222 offset:0x200
	ds_read_b64_tr_b16 v[60:61], v250 offset:0x200
	s_waitcnt lgkmcnt(4)
	v_mfma_f32_16x16x32_bf16 v[62:65], v[10:13], v[22:25], v[62:65]
	v_mfma_f32_16x16x32_bf16 v[22:25], v[14:17], v[22:25], v[166:169]
	ds_read_b64_tr_b16 v[166:167], v220 offset:0x400
	ds_read_b64_tr_b16 v[168:169], v221 offset:0x400
	s_waitcnt lgkmcnt(4)
	v_mfma_f32_16x16x32_bf16 v[66:69], v[10:13], v[26:29], v[66:69]
	v_mfma_f32_16x16x32_bf16 v[26:29], v[14:17], v[26:29], v[162:165]
	ds_read_b64_tr_b16 v[162:163], v222 offset:0x400
	ds_read_b64_tr_b16 v[164:165], v250 offset:0x400
	s_waitcnt lgkmcnt(4)
	v_mfma_f32_16x16x32_bf16 v[70:73], v[10:13], v[58:61], v[70:73]
	v_mfma_f32_16x16x32_bf16 v[58:61], v[14:17], v[58:61], v[154:157]
	ds_read_b64_tr_b16 v[154:155], v220 offset:0x600
	ds_read_b64_tr_b16 v[156:157], v221 offset:0x600
	s_waitcnt lgkmcnt(4)
	v_mfma_f32_16x16x32_bf16 v[178:181], v[10:13], v[166:169], v[74:77]
	v_mfma_f32_16x16x32_bf16 v[150:153], v[14:17], v[166:169], v[150:153]
	ds_read_b64_tr_b16 v[74:75], v222 offset:0x600
	ds_read_b64_tr_b16 v[76:77], v250 offset:0x600
	s_waitcnt lgkmcnt(4)
	v_mfma_f32_16x16x32_bf16 v[166:169], v[10:13], v[162:165], v[82:85]
	v_mfma_f32_16x16x32_bf16 v[162:165], v[14:17], v[162:165], v[142:145]
	ds_read_b64_tr_b16 v[82:83], v220 offset:0x2000
	ds_read_b64_tr_b16 v[84:85], v221 offset:0x2000
	s_waitcnt lgkmcnt(4)
	v_mfma_f32_16x16x32_bf16 v[192:195], v[10:13], v[154:157], v[90:93]
	v_mfma_f32_16x16x32_bf16 v[154:157], v[14:17], v[154:157], v[138:141]
	ds_read_b64_tr_b16 v[90:91], v222 offset:0x2000
	ds_read_b64_tr_b16 v[92:93], v250 offset:0x2000
	s_waitcnt lgkmcnt(4)
	v_mfma_f32_16x16x32_bf16 v[196:199], v[10:13], v[74:77], v[98:101]
	v_mfma_f32_16x16x32_bf16 v[200:203], v[14:17], v[74:77], v[130:133]
	ds_read_b64_tr_b16 v[74:75], v220 offset:0x2200
	ds_read_b64_tr_b16 v[76:77], v221 offset:0x2200
	s_waitcnt lgkmcnt(4)
	v_mfma_f32_16x16x32_bf16 v[110:113], v[10:13], v[82:85], v[110:113]
	v_mfma_f32_16x16x32_bf16 v[126:129], v[14:17], v[82:85], v[126:129]
	ds_read_b64_tr_b16 v[82:83], v222 offset:0x2200
	ds_read_b64_tr_b16 v[84:85], v250 offset:0x2200
	s_waitcnt lgkmcnt(4)
	v_mfma_f32_16x16x32_bf16 v[122:125], v[10:13], v[90:93], v[122:125]
	v_mfma_f32_16x16x32_bf16 v[118:121], v[14:17], v[90:93], v[118:121]
	ds_read_b64_tr_b16 v[90:91], v220 offset:0x2400
	ds_read_b64_tr_b16 v[92:93], v221 offset:0x2400
	s_waitcnt lgkmcnt(4)
	v_mfma_f32_16x16x32_bf16 v[204:207], v[10:13], v[74:77], v[134:137]
	v_mfma_f32_16x16x32_bf16 v[208:211], v[14:17], v[74:77], v[114:117]
	ds_read_b64_tr_b16 v[74:75], v222 offset:0x2400
	ds_read_b64_tr_b16 v[76:77], v250 offset:0x2400
	s_waitcnt lgkmcnt(4)
	v_mfma_f32_16x16x32_bf16 v[212:215], v[10:13], v[82:85], v[146:149]
	v_mfma_f32_16x16x32_bf16 v[216:219], v[14:17], v[82:85], v[106:109]
	ds_read_b64_tr_b16 v[82:83], v220 offset:0x2600
	ds_read_b64_tr_b16 v[84:85], v221 offset:0x2600
	s_waitcnt lgkmcnt(4)
	v_mfma_f32_16x16x32_bf16 v[226:229], v[10:13], v[90:93], v[158:161]
	v_mfma_f32_16x16x32_bf16 v[230:233], v[14:17], v[90:93], v[102:105]
	ds_read_b64_tr_b16 v[90:91], v222 offset:0x2600
	ds_read_b64_tr_b16 v[92:93], v250 offset:0x2600
	s_waitcnt lgkmcnt(4)
	v_mfma_f32_16x16x32_bf16 v[234:237], v[10:13], v[74:77], v[174:177]
	v_mfma_f32_16x16x32_bf16 v[238:241], v[14:17], v[74:77], v[94:97]
	ds_read_b64_tr_b16 v[94:95], v220 offset:0x4000
	ds_read_b64_tr_b16 v[96:97], v221 offset:0x4000
	s_waitcnt lgkmcnt(4)
	v_mfma_f32_16x16x32_bf16 v[242:245], v[10:13], v[82:85], v[182:185]
	v_mfma_f32_16x16x32_bf16 v[246:249], v[14:17], v[82:85], v[86:89]
	ds_read_b64_tr_b16 v[82:83], v222 offset:0x4000
	ds_read_b64_tr_b16 v[84:85], v250 offset:0x4000
	s_waitcnt lgkmcnt(4)
	v_mfma_f32_16x16x32_bf16 v[10:13], v[10:13], v[90:93], v[170:173]
	v_mfma_f32_16x16x32_bf16 v[14:17], v[14:17], v[90:93], v[78:81]
	ds_read_b64_tr_b16 v[86:87], v220 offset:0x4200
	ds_read_b64_tr_b16 v[88:89], v221 offset:0x4200
	s_waitcnt lgkmcnt(4)
	v_mfma_f32_16x16x32_bf16 v[74:77], v[2:5], v[94:97], v[30:33]
	v_mfma_f32_16x16x32_bf16 v[130:133], v[6:9], v[94:97], v[18:21]
	ds_read_b64_tr_b16 v[18:19], v222 offset:0x4200
	ds_read_b64_tr_b16 v[20:21], v250 offset:0x4200
	s_waitcnt lgkmcnt(4)
	v_mfma_f32_16x16x32_bf16 v[78:81], v[2:5], v[82:85], v[62:65]
	v_mfma_f32_16x16x32_bf16 v[134:137], v[6:9], v[82:85], v[22:25]
	ds_read_b64_tr_b16 v[22:23], v220 offset:0x4400
	ds_read_b64_tr_b16 v[24:25], v221 offset:0x4400
	s_waitcnt lgkmcnt(4)
	v_mfma_f32_16x16x32_bf16 v[82:85], v[2:5], v[86:89], v[66:69]
	v_mfma_f32_16x16x32_bf16 v[138:141], v[6:9], v[86:89], v[26:29]
	ds_read_b64_tr_b16 v[26:27], v222 offset:0x4400
	ds_read_b64_tr_b16 v[28:29], v250 offset:0x4400
	s_waitcnt lgkmcnt(4)
	v_mfma_f32_16x16x32_bf16 v[86:89], v[2:5], v[18:21], v[70:73]
	v_mfma_f32_16x16x32_bf16 v[142:145], v[6:9], v[18:21], v[58:61]
	ds_read_b64_tr_b16 v[18:19], v220 offset:0x4600
	ds_read_b64_tr_b16 v[20:21], v221 offset:0x4600
	s_waitcnt lgkmcnt(4)
	v_mfma_f32_16x16x32_bf16 v[90:93], v[2:5], v[22:25], v[178:181]
	v_mfma_f32_16x16x32_bf16 v[146:149], v[6:9], v[22:25], v[150:153]
	ds_read_b64_tr_b16 v[22:23], v222 offset:0x4600
	ds_read_b64_tr_b16 v[24:25], v250 offset:0x4600
	s_waitcnt lgkmcnt(4)
	v_mfma_f32_16x16x32_bf16 v[94:97], v[2:5], v[26:29], v[166:169]
	v_mfma_f32_16x16x32_bf16 v[150:153], v[6:9], v[26:29], v[162:165]
	ds_read_b64_tr_b16 v[26:27], v220 offset:0x6000
	ds_read_b64_tr_b16 v[28:29], v221 offset:0x6000
	s_waitcnt lgkmcnt(4)
	v_mfma_f32_16x16x32_bf16 v[98:101], v[2:5], v[18:21], v[192:195]
	v_mfma_f32_16x16x32_bf16 v[154:157], v[6:9], v[18:21], v[154:157]
	ds_read_b64_tr_b16 v[18:19], v222 offset:0x6000
	ds_read_b64_tr_b16 v[20:21], v250 offset:0x6000
	s_waitcnt lgkmcnt(4)
	v_mfma_f32_16x16x32_bf16 v[102:105], v[2:5], v[22:25], v[196:199]
	v_mfma_f32_16x16x32_bf16 v[158:161], v[6:9], v[22:25], v[200:203]
	ds_read_b64_tr_b16 v[22:23], v220 offset:0x6200
	ds_read_b64_tr_b16 v[24:25], v221 offset:0x6200
	s_waitcnt lgkmcnt(4)
	v_mfma_f32_16x16x32_bf16 v[106:109], v[2:5], v[26:29], v[110:113]
	v_mfma_f32_16x16x32_bf16 v[162:165], v[6:9], v[26:29], v[126:129]
	ds_read_b64_tr_b16 v[26:27], v222 offset:0x6200
	ds_read_b64_tr_b16 v[28:29], v250 offset:0x6200
	s_waitcnt lgkmcnt(4)
	v_mfma_f32_16x16x32_bf16 v[110:113], v[2:5], v[18:21], v[122:125]
	v_mfma_f32_16x16x32_bf16 v[166:169], v[6:9], v[18:21], v[118:121]
	ds_read_b64_tr_b16 v[18:19], v220 offset:0x6400
	ds_read_b64_tr_b16 v[20:21], v221 offset:0x6400
	s_waitcnt lgkmcnt(4)
	v_mfma_f32_16x16x32_bf16 v[114:117], v[2:5], v[22:25], v[204:207]
	v_mfma_f32_16x16x32_bf16 v[170:173], v[6:9], v[22:25], v[208:211]
	ds_read_b64_tr_b16 v[22:23], v222 offset:0x6400
	ds_read_b64_tr_b16 v[24:25], v250 offset:0x6400
	s_waitcnt lgkmcnt(4)
	v_mfma_f32_16x16x32_bf16 v[118:121], v[2:5], v[26:29], v[212:215]
	v_mfma_f32_16x16x32_bf16 v[174:177], v[6:9], v[26:29], v[216:219]
	ds_read_b64_tr_b16 v[26:27], v220 offset:0x6600
	ds_read_b64_tr_b16 v[28:29], v221 offset:0x6600
	s_waitcnt lgkmcnt(4)
	v_mfma_f32_16x16x32_bf16 v[122:125], v[2:5], v[18:21], v[226:229]
	v_mfma_f32_16x16x32_bf16 v[178:181], v[6:9], v[18:21], v[230:233]
	ds_read_b64_tr_b16 v[18:19], v222 offset:0x6600
	ds_read_b64_tr_b16 v[20:21], v250 offset:0x6600
	s_waitcnt lgkmcnt(4)
	v_mfma_f32_16x16x32_bf16 v[126:129], v[2:5], v[22:25], v[234:237]
	v_mfma_f32_16x16x32_bf16 v[182:185], v[6:9], v[22:25], v[238:241]
	s_waitcnt lgkmcnt(2)
	v_mfma_f32_16x16x32_bf16 v[66:69], v[2:5], v[26:29], v[242:245]
	v_mfma_f32_16x16x32_bf16 v[70:73], v[6:9], v[26:29], v[246:249]
	s_waitcnt lgkmcnt(0)
	v_mfma_f32_16x16x32_bf16 v[58:61], v[2:5], v[18:21], v[10:13]
	v_mfma_f32_16x16x32_bf16 v[62:65], v[6:9], v[18:21], v[14:17]
	s_cmp_ge_u32 s89, s80
	s_waitcnt vmcnt(0)
	s_barrier
	s_cselect_b64 s[34:35], -1, 0
	s_and_b64 vcc, exec, s[34:35]
	v_mbcnt_lo_u32_b32 v192, -1, 0
	v_mbcnt_hi_u32_b32 v192, -1, v192
	s_cbranch_vccnz .LBB0_194
	s_add_u32 s98, s8, s30
	s_addc_u32 s99, s9, s31
	s_mov_b32 m0, s62
	s_addk_i32 s36, 0x80
	global_load_lds_dwordx4 v251, s[98:99]
	s_mov_b32 m0, s63
	s_mul_hi_i32 s37, s36, 0xa000
	global_load_lds_dwordx4 v251, s[8:9]
	s_mov_b32 m0, s66
	s_mul_i32 s36, s36, 0xa000
	global_load_lds_dwordx4 v252, s[98:99]
	s_mov_b32 m0, s67
	s_add_u32 s36, s82, s36
	global_load_lds_dwordx4 v252, s[8:9]
	s_addc_u32 s37, s83, s37
	s_add_u32 s98, s36, 0x80
	s_addc_u32 s99, s37, 0
	s_mov_b32 m0, s71
	s_nop 0
	global_load_lds_dwordx4 v253, s[36:37]
	s_mov_b32 m0, s72
	s_nop 0
	global_load_lds_dwordx4 v253, s[98:99]
	s_mov_b32 m0, s75
	s_nop 0
	global_load_lds_dwordx4 v254, s[36:37]
	s_mov_b32 m0, s78
	s_nop 0
	global_load_lds_dwordx4 v254, s[98:99]

	.amdhsa_kernel _Z3fwd4Args
		.amdhsa_group_segment_fixed_size 0
		.amdhsa_private_segment_fixed_size 0
		.amdhsa_kernarg_size 432
		.amdhsa_user_sgpr_count 2
		.amdhsa_user_sgpr_dispatch_ptr 0
		.amdhsa_user_sgpr_queue_ptr 0
		.amdhsa_user_sgpr_kernarg_segment_ptr 1
		.amdhsa_user_sgpr_dispatch_id 0
		.amdhsa_user_sgpr_kernarg_preload_length 0
		.amdhsa_user_sgpr_kernarg_preload_offset 0
		.amdhsa_user_sgpr_private_segment_size 0
		.amdhsa_uses_dynamic_stack 0
		.amdhsa_enable_private_segment 0
		.amdhsa_system_sgpr_workgroup_id_x 1
		.amdhsa_system_sgpr_workgroup_id_y 0
		.amdhsa_system_sgpr_workgroup_id_z 0
		.amdhsa_system_sgpr_workgroup_info 0
		.amdhsa_system_vgpr_workitem_id 0
		.amdhsa_next_free_vgpr 256
		.amdhsa_next_free_sgpr 102
		.amdhsa_accum_offset 256
		.amdhsa_reserve_vcc 1
		.amdhsa_float_round_mode_32 0
		.amdhsa_float_round_mode_16_64 0
		.amdhsa_float_denorm_mode_32 3
		.amdhsa_float_denorm_mode_16_64 3
		.amdhsa_dx10_clamp 1
		.amdhsa_ieee_mode 1
		.amdhsa_fp16_overflow 0
		.amdhsa_tg_split 0
		.amdhsa_exception_fp_ieee_invalid_op 0
		.amdhsa_exception_fp_denorm_src 0
		.amdhsa_exception_fp_ieee_div_zero 0
		.amdhsa_exception_fp_ieee_overflow 0
		.amdhsa_exception_fp_ieee_underflow 0
		.amdhsa_exception_fp_ieee_inexact 0
		.amdhsa_exception_int_div_zero 0
	.end_amdhsa_kernel

amdhsa.kernels:
  - .agpr_count:     0
    .args:
      - .offset:         0
        .size:           176
        .value_kind:     by_value
      - .offset:         176
        .size:           4
        .value_kind:     hidden_block_count_x
      - .offset:         180
        .size:           4
        .value_kind:     hidden_block_count_y
      - .offset:         184
        .size:           4
        .value_kind:     hidden_block_count_z
      - .offset:         188
        .size:           2
        .value_kind:     hidden_group_size_x
      - .offset:         190
        .size:           2
        .value_kind:     hidden_group_size_y
      - .offset:         192
        .size:           2
        .value_kind:     hidden_group_size_z
      - .offset:         194
        .size:           2
        .value_kind:     hidden_remainder_x
      - .offset:         196
        .size:           2
        .value_kind:     hidden_remainder_y
      - .offset:         198
        .size:           2
        .value_kind:     hidden_remainder_z
      - .offset:         216
        .size:           8
        .value_kind:     hidden_global_offset_x
      - .offset:         224
        .size:           8
        .value_kind:     hidden_global_offset_y
      - .offset:         232
        .size:           8
        .value_kind:     hidden_global_offset_z
      - .offset:         240
        .size:           2
        .value_kind:     hidden_grid_dims
      - .offset:         296
        .size:           4
        .value_kind:     hidden_dynamic_lds_size
    .group_segment_fixed_size: 0
    .kernarg_segment_align: 8
    .kernarg_segment_size: 432
    .language:       OpenCL C
    .language_version:
      - 2
      - 0
    .max_flat_workgroup_size: 512
    .name:           _Z3fwd4Args
    .private_segment_fixed_size: 0
    .sgpr_count:     108
    .sgpr_spill_count: 0
    .symbol:         _Z3fwd4Args.kd
    .uniform_work_group_size: 1
    .uses_dynamic_stack: false
    .vgpr_count:     256
    .vgpr_spill_count: 0
    .wavefront_size: 64
